# XN stores write-through (sc1) instead of plain: less dirty L2 to flush at the first grid barrier
# baseline (speedup 1.0000x reference)
; __device__ __forceinline__ unsigned cvt_pk_bf16(float lo, float hi) { unsigned r; asm volatile("v_cvt_pk_bf16_f32 %0, %1, %2" : "=v"(r) : "v"(lo), "v"(hi)); return r; }
; __device__ __forceinline__ void p0_prologue(const Params& p, unsigned char* lds) {
;     ...
;         for (int m0 = 4 * gw; m0 < MT; m0 += 4 * NGW) {
;             int mm[4]; const float* xr[4];
; #pragma unroll
;             for (int q = 0; q < 4; ++q) { mm[q] = m0 + q;
;                 xr[q] = mm[q] < MP ? p.in[I_XP] + (size_t)mm[q] * DM : p.in[I_XS] + (size_t)(mm[q] - MP) * DM; }
;             f32x4 v[4][4];
; #pragma unroll
;             for (int q = 0; q < 4; ++q)
; #pragma unroll
;                 for (int j = 0; j < 4; ++j) v[q][j] = __builtin_nontemporal_load((const f32x4*)xr[q] + lane + 64 * j);
; #pragma unroll
;             for (int q = 0; q < 4; ++q) { float s = 0.f;
; #pragma unroll
;                 for (int j = 0; j < 4; ++j) s += (v[q][j][0] * v[q][j][0] + v[q][j][1] * v[q][j][1]) + (v[q][j][2] * v[q][j][2] + v[q][j][3] * v[q][j][3]);
;                 const float rstd = rsqrtf(wave_sum(s) * (1.0f / DM) + EPS);
;                 u32x2* o8 = (u32x2*)(XN + (size_t)mm[q] * DM) + lane;
; #pragma unroll
;                 for (int j = 0; j < 4; ++j) { u32x2 o; o.x = cvt_pk_bf16(v[q][j][0] * rstd * gv[j][0], v[q][j][1] * rstd * gv[j][1]); o.y = cvt_pk_bf16(v[q][j][2] * rstd * gv[j][2], v[q][j][3] * rstd * gv[j][3]); __builtin_nontemporal_store(o, o8 + 64 * j); } }
.LBB0_76:
	s_or_b64 exec, exec, s[4:5]
	v_add_u32_e32 v20, 0xffffbfff, v54
	v_lshl_add_u64 v[18:19], v[54:55], 0, -1
	v_cmp_gt_i32_e32 vcc, s1, v50
	v_lshl_add_u64 v[16:17], v[16:17], 0, v[178:179]
	v_lshl_add_u64 v[34:35], v[54:55], 0, 1
	v_cndmask_b32_e32 v19, 0, v19, vcc
	v_cndmask_b32_e32 v18, v20, v18, vcc
	v_cndmask_b32_e32 v21, v62, v63, vcc
	v_cndmask_b32_e32 v20, v64, v65, vcc
	v_lshlrev_b64 v[18:19], 12, v[18:19]
	v_lshl_add_u64 v[18:19], v[20:21], 0, v[18:19]
	v_lshl_add_u64 v[18:19], v[18:19], 0, v[178:179]
	global_load_dwordx4 v[66:69], v[18:19], off nt
	global_load_dwordx4 v[70:73], v[18:19], off offset:1024 nt
	global_load_dwordx4 v[74:77], v[18:19], off offset:3072 nt
	global_load_dwordx4 v[78:81], v[18:19], off offset:2048 nt
	v_add_u32_e32 v18, 0xffffc000, v54
	v_cmp_gt_i32_e32 vcc, s1, v54
	v_add_u32_e32 v38, 0xffffc001, v54
	v_add_co_u32_e64 v98, s[4:5], s16, v58
	v_cndmask_b32_e32 v33, 0, v55, vcc
	v_cndmask_b32_e32 v32, v18, v54, vcc
	v_cndmask_b32_e32 v37, v62, v63, vcc
	v_cndmask_b32_e32 v36, v64, v65, vcc
	v_lshlrev_b64 v[32:33], 12, v[32:33]
	v_lshl_add_u64 v[32:33], v[36:37], 0, v[32:33]
	v_lshl_add_u64 v[32:33], v[32:33], 0, v[178:179]
	global_load_dwordx4 v[28:31], v[16:17], off nt
	global_load_dwordx4 v[24:27], v[16:17], off offset:1024 nt
	global_load_dwordx4 v[20:23], v[16:17], off offset:2048 nt
	s_nop 0
	global_load_dwordx4 v[16:19], v[16:17], off offset:3072 nt
	s_nop 0
	global_load_dwordx4 v[82:85], v[32:33], off nt
	global_load_dwordx4 v[86:89], v[32:33], off offset:1024 nt
	global_load_dwordx4 v[90:93], v[32:33], off offset:2048 nt
	global_load_dwordx4 v[94:97], v[32:33], off offset:3072 nt
	v_cmp_gt_i32_e32 vcc, s1, v34
	v_addc_co_u32_e64 v99, s[4:5], -1, v59, s[4:5]
	s_nop 0
	v_cndmask_b32_e32 v35, 0, v35, vcc
	v_cndmask_b32_e32 v34, v38, v34, vcc
	v_cndmask_b32_e32 v39, v62, v63, vcc
	v_cndmask_b32_e32 v38, v64, v65, vcc
	v_lshlrev_b64 v[34:35], 12, v[34:35]
	v_lshl_add_u64 v[34:35], v[38:39], 0, v[34:35]
	v_lshl_add_u64 v[32:33], v[34:35], 0, v[178:179]
	v_add_u32_e32 v50, s8, v50
	v_lshl_add_u64 v[54:55], v[54:55], 0, s[8:9]
	v_lshl_add_u64 v[56:57], v[56:57], 0, s[10:11]
	s_waitcnt vmcnt(11)
	v_pk_mul_f32 v[34:35], v[68:69], v[68:69]
	v_pk_mul_f32 v[36:37], v[66:67], v[66:67]
	s_waitcnt vmcnt(10)
	v_pk_mul_f32 v[38:39], v[72:73], v[72:73]
	v_pk_mul_f32 v[40:41], v[70:71], v[70:71]
	v_pk_mov_b32 v[46:47], v[36:37], v[34:35] op_sel:[1,0]
	v_mov_b32_e32 v37, v35
	v_pk_mov_b32 v[34:35], v[40:41], v[38:39] op_sel:[1,0]
	v_mov_b32_e32 v41, v39
	s_waitcnt vmcnt(9)
	v_mul_f32_e32 v45, v74, v74
	s_waitcnt vmcnt(8)
	v_mul_f32_e32 v42, v79, v79
	v_mul_f32_e32 v44, v81, v81
	v_pk_add_f32 v[36:37], v[46:47], v[36:37]
	v_pk_add_f32 v[34:35], v[34:35], v[40:41]
	v_mul_f32_e32 v48, v75, v75
	v_mul_f32_e32 v100, v76, v76
	v_mul_f32_e32 v101, v77, v77
	v_pk_fma_f32 v[38:39], v[78:79], v[78:79], v[42:43] op_sel_hi:[1,1,0]
	v_pk_fma_f32 v[42:43], v[80:81], v[80:81], v[44:45] op_sel_hi:[1,1,0]
	v_pk_add_f32 v[36:37], v[36:37], v[36:37] op_sel:[0,1] op_sel_hi:[1,0]
	v_pk_add_f32 v[34:35], v[34:35], v[34:35] op_sel:[0,1] op_sel_hi:[1,0]
	v_mov_b32_e32 v39, v100
	v_mov_b32_e32 v43, v101
	v_mov_b32_e32 v37, v45
	v_mov_b32_e32 v35, v48
	v_pk_add_f32 v[38:39], v[38:39], v[42:43]
	v_pk_add_f32 v[34:35], v[36:37], v[34:35]
	s_nop 0
	v_pk_add_f32 v[34:35], v[34:35], v[38:39]
	s_nop 0
	v_add_f32_e32 v34, v34, v35
	s_nop 1
	v_add_f32_dpp v34, v34, v34 quad_perm:[1,0,3,2] row_mask:0xf bank_mask:0xf bound_ctrl:1
	s_nop 1
	v_add_f32_dpp v34, v34, v34 quad_perm:[2,3,0,1] row_mask:0xf bank_mask:0xf bound_ctrl:1
	s_nop 1
	v_add_f32_dpp v34, v34, v34 row_half_mirror row_mask:0xf bank_mask:0xf bound_ctrl:1
	s_nop 1
	v_add_f32_dpp v34, v34, v34 row_mirror row_mask:0xf bank_mask:0xf bound_ctrl:1
	s_nop 0
	v_readlane_b32 s18, v34, 16
	v_readlane_b32 s19, v34, 48
	v_readlane_b32 s4, v34, 0
	v_readlane_b32 s5, v34, 32
	v_mov_b32_e32 v34, s18
	v_mov_b32_e32 v35, s19
	v_pk_add_f32 v[34:35], s[4:5], v[34:35]
	s_nop 0
	v_add_f32_e32 v34, v34, v35
	v_fmamk_f32 v34, v34, 0x3a800000, v51
	v_mul_f32_e32 v35, 0x4b800000, v34
	v_cmp_gt_f32_e32 vcc, s3, v34
	s_nop 1
	v_cndmask_b32_e32 v34, v34, v35, vcc
	v_rsq_f32_e32 v48, v34
	global_load_dwordx4 v[44:47], v[32:33], off nt
	global_load_dwordx4 v[40:43], v[32:33], off offset:1024 nt
	global_load_dwordx4 v[36:39], v[32:33], off offset:2048 nt
	s_nop 0
	global_load_dwordx4 v[32:35], v[32:33], off offset:3072 nt
	v_mul_f32_e32 v100, 0x45800000, v48
	v_cndmask_b32_e32 v48, v48, v100, vcc
	v_mul_f32_e32 v66, v66, v48
	v_mul_f32_e32 v67, v67, v48
	v_mul_f32_e32 v68, v68, v48
	v_mul_f32_e32 v69, v69, v48
	v_mul_f32_e32 v66, v12, v66
	v_mul_f32_e32 v67, v13, v67
	v_mul_f32_e32 v72, v72, v48
	v_mul_f32_e32 v68, v14, v68
	v_mul_f32_e32 v69, v15, v69
	v_cvt_pk_bf16_f32 v66, v66, v67
	v_cvt_pk_bf16_f32 v67, v68, v69
	v_mul_f32_e32 v70, v70, v48
	v_mul_f32_e32 v71, v71, v48
	global_store_dwordx2 v[98:99], v[66:67], off offset:-1536 sc1
	v_mul_f32_e32 v67, v10, v72
	v_mul_f32_e32 v68, v73, v48
	v_mul_f32_e32 v70, v8, v70
	v_mul_f32_e32 v71, v9, v71
	v_cvt_pk_bf16_f32 v66, v70, v71
	v_mul_f32_e32 v68, v11, v68
	v_cvt_pk_bf16_f32 v67, v67, v68
	global_store_dwordx2 v[98:99], v[66:67], off offset:-1024 sc1
	v_mul_f32_e32 v66, v78, v48
	v_mul_f32_e32 v67, v79, v48
	v_mul_f32_e32 v66, v4, v66
	v_mul_f32_e32 v67, v5, v67
	v_cvt_pk_bf16_f32 v66, v66, v67
	v_mul_f32_e32 v67, v80, v48
	v_mul_f32_e32 v68, v81, v48
	v_mul_f32_e32 v67, v6, v67
	v_mul_f32_e32 v68, v7, v68
	v_cvt_pk_bf16_f32 v67, v67, v68
	s_waitcnt vmcnt(9)
; __device__ __forceinline__ unsigned cvt_pk_bf16(float lo, float hi) { unsigned r; asm volatile("v_cvt_pk_bf16_f32 %0, %1, %2" : "=v"(r) : "v"(lo), "v"(hi)); return r; }
; __device__ __forceinline__ void p0_prologue(const Params& p, unsigned char* lds) {
;     ...
;             for (int q = 0; q < 4; ++q) { float s = 0.f;
; #pragma unroll
;                 for (int j = 0; j < 4; ++j) s += (v[q][j][0] * v[q][j][0] + v[q][j][1] * v[q][j][1]) + (v[q][j][2] * v[q][j][2] + v[q][j][3] * v[q][j][3]);
;                 const float rstd = rsqrtf(wave_sum(s) * (1.0f / DM) + EPS);
;                 u32x2* o8 = (u32x2*)(XN + (size_t)mm[q] * DM) + lane;
; #pragma unroll
;                 for (int j = 0; j < 4; ++j) { u32x2 o; o.x = cvt_pk_bf16(v[q][j][0] * rstd * gv[j][0], v[q][j][1] * rstd * gv[j][1]); o.y = cvt_pk_bf16(v[q][j][2] * rstd * gv[j][2], v[q][j][3] * rstd * gv[j][3]); __builtin_nontemporal_store(o, o8 + 64 * j); } }
	v_pk_mul_f32 v[68:69], v[84:85], v[84:85]
	v_pk_mul_f32 v[70:71], v[82:83], v[82:83]
	global_store_dwordx2 v[98:99], v[66:67], off offset:-512 sc1
	v_pk_mov_b32 v[72:73], v[70:71], v[68:69] op_sel:[1,0]
	v_mov_b32_e32 v71, v69
	v_pk_add_f32 v[68:69], v[72:73], v[70:71]
	s_waitcnt vmcnt(9)
	v_pk_mul_f32 v[70:71], v[88:89], v[88:89]
	v_pk_mul_f32 v[72:73], v[86:87], v[86:87]
	v_mul_f32_e32 v66, v74, v48
	v_mul_f32_e32 v67, v75, v48
	v_pk_mov_b32 v[74:75], v[72:73], v[70:71] op_sel:[1,0]
	v_mov_b32_e32 v73, v71
	v_mul_f32_e32 v66, v0, v66
	v_mul_f32_e32 v67, v1, v67
	v_pk_add_f32 v[70:71], v[74:75], v[72:73]
	v_cvt_pk_bf16_f32 v66, v66, v67
	v_mul_f32_e32 v67, v76, v48
	v_mul_f32_e32 v76, v77, v48
	s_waitcnt vmcnt(7)
	v_mul_f32_e32 v48, v94, v94
	v_mul_f32_e32 v72, v95, v95
	v_pk_add_f32 v[68:69], v[68:69], v[68:69] op_sel:[0,1] op_sel_hi:[1,0]
	v_pk_add_f32 v[70:71], v[70:71], v[70:71] op_sel:[0,1] op_sel_hi:[1,0]
	v_mov_b32_e32 v69, v48
	v_mov_b32_e32 v71, v72
	v_mul_f32_e32 v48, v91, v91
	v_mul_f32_e32 v73, v96, v96
	v_pk_add_f32 v[68:69], v[68:69], v[70:71]
	v_pk_fma_f32 v[70:71], v[90:91], v[90:91], v[48:49] op_sel_hi:[1,1,0]
	v_mul_f32_e32 v48, v93, v93
	v_mul_f32_e32 v74, v97, v97
	v_mov_b32_e32 v71, v73
	v_pk_fma_f32 v[72:73], v[92:93], v[92:93], v[48:49] op_sel_hi:[1,1,0]
	v_mul_f32_e32 v67, v2, v67
	v_mov_b32_e32 v73, v74
	v_pk_add_f32 v[70:71], v[70:71], v[72:73]
	s_nop 0
	v_pk_add_f32 v[68:69], v[68:69], v[70:71]
	s_waitcnt vmcnt(6)
	v_pk_mul_f32 v[70:71], v[44:45], v[44:45]
	v_add_f32_e32 v48, v68, v69
	s_nop 1
	v_add_f32_dpp v48, v48, v48 quad_perm:[1,0,3,2] row_mask:0xf bank_mask:0xf bound_ctrl:1
	s_nop 1
	v_add_f32_dpp v48, v48, v48 quad_perm:[2,3,0,1] row_mask:0xf bank_mask:0xf bound_ctrl:1
	s_nop 1
	v_add_f32_dpp v48, v48, v48 row_half_mirror row_mask:0xf bank_mask:0xf bound_ctrl:1
	s_nop 1
	v_add_f32_dpp v48, v48, v48 row_mirror row_mask:0xf bank_mask:0xf bound_ctrl:1
	s_nop 0
	v_readlane_b32 s18, v48, 16
	v_readlane_b32 s19, v48, 48
	v_readlane_b32 s4, v48, 0
	v_readlane_b32 s5, v48, 32
	v_mov_b32_e32 v68, s18
	v_mov_b32_e32 v69, s19
	v_pk_add_f32 v[68:69], s[4:5], v[68:69]
	s_nop 0
	v_add_f32_e32 v48, v68, v69
	v_fmamk_f32 v48, v48, 0x3a800000, v51
	v_mul_f32_e32 v68, 0x4b800000, v48
	v_cmp_gt_f32_e32 vcc, s3, v48
	s_nop 1
	v_cndmask_b32_e32 v48, v48, v68, vcc
	v_rsq_f32_e32 v48, v48
	v_mul_f32_e32 v68, v3, v76
	v_cvt_pk_bf16_f32 v67, v67, v68
	global_store_dwordx2 v[58:59], v[66:67], off offset:-4096 sc1
	v_mul_f32_e32 v66, 0x45800000, v48
	v_cndmask_b32_e32 v48, v48, v66, vcc
	v_mul_f32_e32 v66, v82, v48
	v_mul_f32_e32 v67, v83, v48
	v_mul_f32_e32 v66, v12, v66
	v_mul_f32_e32 v67, v13, v67
	v_cvt_pk_bf16_f32 v66, v66, v67
	v_mul_f32_e32 v67, v84, v48
	v_mul_f32_e32 v67, v14, v67
	v_mul_f32_e32 v68, v85, v48
	v_mul_f32_e32 v68, v15, v68
	v_cvt_pk_bf16_f32 v67, v67, v68
	global_store_dwordx2 v[58:59], v[66:67], off offset:-3584 sc1
	v_mul_f32_e32 v66, v86, v48
	v_mul_f32_e32 v67, v87, v48
	v_mul_f32_e32 v66, v8, v66
	v_mul_f32_e32 v67, v9, v67
	v_cvt_pk_bf16_f32 v66, v66, v67
	v_mul_f32_e32 v67, v88, v48
	v_mul_f32_e32 v67, v10, v67
	v_mul_f32_e32 v68, v89, v48
	v_mul_f32_e32 v68, v11, v68
	v_cvt_pk_bf16_f32 v67, v67, v68
	global_store_dwordx2 v[58:59], v[66:67], off offset:-3072 sc1
	v_mul_f32_e32 v66, v90, v48
	v_mul_f32_e32 v67, v91, v48
	v_mul_f32_e32 v66, v4, v66
	v_mul_f32_e32 v67, v5, v67
	v_cvt_pk_bf16_f32 v66, v66, v67
	v_mul_f32_e32 v67, v92, v48
	v_mul_f32_e32 v68, v93, v48
	v_mul_f32_e32 v67, v6, v67
	v_mul_f32_e32 v68, v7, v68
	v_cvt_pk_bf16_f32 v67, v67, v68
	v_pk_mul_f32 v[68:69], v[46:47], v[46:47]
	global_store_dwordx2 v[58:59], v[66:67], off offset:-2560 sc1
	v_pk_mov_b32 v[72:73], v[70:71], v[68:69] op_sel:[1,0]
	v_mov_b32_e32 v71, v69
	v_pk_add_f32 v[68:69], v[72:73], v[70:71]
	s_waitcnt vmcnt(9)
	v_pk_mul_f32 v[70:71], v[42:43], v[42:43]
	v_pk_mul_f32 v[72:73], v[40:41], v[40:41]
	v_mul_f32_e32 v66, v94, v48
	v_mul_f32_e32 v67, v95, v48
	v_pk_mov_b32 v[74:75], v[72:73], v[70:71] op_sel:[1,0]
	v_mov_b32_e32 v73, v71
	v_mul_f32_e32 v66, v0, v66
	v_mul_f32_e32 v67, v1, v67
	v_pk_add_f32 v[70:71], v[74:75], v[72:73]
	v_cvt_pk_bf16_f32 v66, v66, v67
	v_mul_f32_e32 v67, v96, v48
	v_mul_f32_e32 v76, v97, v48
	s_waitcnt vmcnt(7)
; __device__ __forceinline__ unsigned cvt_pk_bf16(float lo, float hi) { unsigned r; asm volatile("v_cvt_pk_bf16_f32 %0, %1, %2" : "=v"(r) : "v"(lo), "v"(hi)); return r; }
; __device__ __forceinline__ void p0_prologue(const Params& p, unsigned char* lds) {
;     ...
;             for (int q = 0; q < 4; ++q) { float s = 0.f;
; #pragma unroll
;                 for (int j = 0; j < 4; ++j) s += (v[q][j][0] * v[q][j][0] + v[q][j][1] * v[q][j][1]) + (v[q][j][2] * v[q][j][2] + v[q][j][3] * v[q][j][3]);
;                 const float rstd = rsqrtf(wave_sum(s) * (1.0f / DM) + EPS);
;                 u32x2* o8 = (u32x2*)(XN + (size_t)mm[q] * DM) + lane;
; #pragma unroll
;                 for (int j = 0; j < 4; ++j) { u32x2 o; o.x = cvt_pk_bf16(v[q][j][0] * rstd * gv[j][0], v[q][j][1] * rstd * gv[j][1]); o.y = cvt_pk_bf16(v[q][j][2] * rstd * gv[j][2], v[q][j][3] * rstd * gv[j][3]); __builtin_nontemporal_store(o, o8 + 64 * j); } }
	v_mul_f32_e32 v48, v32, v32
	v_mul_f32_e32 v72, v33, v33
	v_pk_add_f32 v[68:69], v[68:69], v[68:69] op_sel:[0,1] op_sel_hi:[1,0]
	v_pk_add_f32 v[70:71], v[70:71], v[70:71] op_sel:[0,1] op_sel_hi:[1,0]
	v_mov_b32_e32 v69, v48
	v_mov_b32_e32 v71, v72
	v_mul_f32_e32 v48, v37, v37
	v_mul_f32_e32 v73, v34, v34
	v_pk_add_f32 v[68:69], v[68:69], v[70:71]
	v_pk_fma_f32 v[70:71], v[36:37], v[36:37], v[48:49] op_sel_hi:[1,1,0]
	v_mul_f32_e32 v48, v39, v39
	v_mul_f32_e32 v74, v35, v35
	v_mov_b32_e32 v71, v73
	v_pk_fma_f32 v[72:73], v[38:39], v[38:39], v[48:49] op_sel_hi:[1,1,0]
	v_mul_f32_e32 v67, v2, v67
	v_mov_b32_e32 v73, v74
	v_pk_add_f32 v[70:71], v[70:71], v[72:73]
	s_nop 0
	v_pk_add_f32 v[68:69], v[68:69], v[70:71]
	s_nop 0
	v_add_f32_e32 v48, v68, v69
	s_nop 1
	v_add_f32_dpp v48, v48, v48 quad_perm:[1,0,3,2] row_mask:0xf bank_mask:0xf bound_ctrl:1
	s_nop 1
	v_add_f32_dpp v48, v48, v48 quad_perm:[2,3,0,1] row_mask:0xf bank_mask:0xf bound_ctrl:1
	s_nop 1
	v_add_f32_dpp v48, v48, v48 row_half_mirror row_mask:0xf bank_mask:0xf bound_ctrl:1
	s_nop 1
	v_add_f32_dpp v48, v48, v48 row_mirror row_mask:0xf bank_mask:0xf bound_ctrl:1
	s_nop 0
	v_readlane_b32 s18, v48, 16
	v_readlane_b32 s19, v48, 48
	v_readlane_b32 s4, v48, 0
	v_readlane_b32 s5, v48, 32
	v_mov_b32_e32 v68, s18
	v_mov_b32_e32 v69, s19
	v_pk_add_f32 v[68:69], s[4:5], v[68:69]
	s_nop 0
	v_add_f32_e32 v48, v68, v69
	v_fmamk_f32 v48, v48, 0x3a800000, v51
	v_mul_f32_e32 v68, 0x4b800000, v48
	v_cmp_gt_f32_e32 vcc, s3, v48
	s_nop 1
	v_cndmask_b32_e32 v48, v48, v68, vcc
	v_rsq_f32_e32 v48, v48
	v_mul_f32_e32 v68, v3, v76
	v_cvt_pk_bf16_f32 v67, v67, v68
	global_store_dwordx2 v[58:59], v[66:67], off offset:-2048 sc1
	v_mul_f32_e32 v66, 0x45800000, v48
	v_cndmask_b32_e32 v48, v48, v66, vcc
	v_mul_f32_e32 v44, v44, v48
	v_mul_f32_e32 v45, v45, v48
	v_mul_f32_e32 v44, v12, v44
	v_mul_f32_e32 v45, v13, v45
	v_cvt_pk_bf16_f32 v44, v44, v45
	v_mul_f32_e32 v45, v46, v48
	v_mul_f32_e32 v40, v40, v48
	v_mul_f32_e32 v41, v41, v48
	v_mul_f32_e32 v45, v14, v45
	v_mul_f32_e32 v46, v47, v48
	v_mul_f32_e32 v40, v8, v40
	v_mul_f32_e32 v41, v9, v41
	v_mul_f32_e32 v46, v15, v46
	v_cvt_pk_bf16_f32 v45, v45, v46
	global_store_dwordx2 v[58:59], v[44:45], off offset:-1536 sc1
	v_cvt_pk_bf16_f32 v40, v40, v41
	v_mul_f32_e32 v41, v42, v48
	v_mul_f32_e32 v36, v36, v48
	v_mul_f32_e32 v37, v37, v48
	v_mul_f32_e32 v41, v10, v41
	v_mul_f32_e32 v42, v43, v48
	v_mul_f32_e32 v36, v4, v36
	v_mul_f32_e32 v37, v5, v37
	v_mul_f32_e32 v42, v11, v42
	v_cvt_pk_bf16_f32 v41, v41, v42
	global_store_dwordx2 v[58:59], v[40:41], off offset:-1024 sc1
	v_cvt_pk_bf16_f32 v36, v36, v37
	v_mul_f32_e32 v37, v38, v48
	v_mul_f32_e32 v37, v6, v37
	v_mul_f32_e32 v38, v39, v48
	v_mul_f32_e32 v32, v32, v48
	v_mul_f32_e32 v33, v33, v48
	v_mul_f32_e32 v38, v7, v38
	v_cvt_pk_bf16_f32 v37, v37, v38
	v_mul_f32_e32 v32, v0, v32
	v_mul_f32_e32 v33, v1, v33
	global_store_dwordx2 v[58:59], v[36:37], off offset:-512 sc1
	v_cvt_pk_bf16_f32 v32, v32, v33
	v_mul_f32_e32 v33, v34, v48
	v_mul_f32_e32 v42, v35, v48
	v_pk_mul_f32 v[34:35], v[30:31], v[30:31]
	v_pk_mul_f32 v[36:37], v[28:29], v[28:29]
	v_mul_f32_e32 v33, v2, v33
	v_pk_mov_b32 v[38:39], v[36:37], v[34:35] op_sel:[1,0]
	v_mov_b32_e32 v37, v35
	v_pk_add_f32 v[34:35], v[38:39], v[36:37]
	v_pk_mul_f32 v[36:37], v[26:27], v[26:27]
	v_pk_mul_f32 v[38:39], v[24:25], v[24:25]
	v_pk_add_f32 v[34:35], v[34:35], v[34:35] op_sel:[0,1] op_sel_hi:[1,0]
	v_pk_mov_b32 v[40:41], v[38:39], v[36:37] op_sel:[1,0]
	v_mov_b32_e32 v39, v37
	v_pk_add_f32 v[36:37], v[40:41], v[38:39]
	v_mul_f32_e32 v38, v16, v16
	v_mul_f32_e32 v39, v17, v17
	v_pk_add_f32 v[36:37], v[36:37], v[36:37] op_sel:[0,1] op_sel_hi:[1,0]
	v_mov_b32_e32 v35, v38
	v_mov_b32_e32 v37, v39
	v_pk_add_f32 v[34:35], v[34:35], v[36:37]
	v_mul_f32_e32 v36, v21, v21
	v_mul_f32_e32 v38, v23, v23
	v_mul_f32_e32 v40, v18, v18
	v_mul_f32_e32 v41, v19, v19
	v_pk_fma_f32 v[36:37], v[20:21], v[20:21], v[36:37] op_sel_hi:[1,1,0]
	v_pk_fma_f32 v[38:39], v[22:23], v[22:23], v[38:39] op_sel_hi:[1,1,0]
	v_mov_b32_e32 v37, v40
	v_mov_b32_e32 v39, v41
	v_pk_add_f32 v[36:37], v[36:37], v[38:39]
	s_nop 0
	v_pk_add_f32 v[34:35], v[34:35], v[36:37]
	s_nop 0
	v_add_f32_e32 v34, v34, v35
	s_nop 1
	v_add_f32_dpp v34, v34, v34 quad_perm:[1,0,3,2] row_mask:0xf bank_mask:0xf bound_ctrl:1
	s_nop 1
	v_add_f32_dpp v34, v34, v34 quad_perm:[2,3,0,1] row_mask:0xf bank_mask:0xf bound_ctrl:1
	s_nop 1
	v_add_f32_dpp v34, v34, v34 row_half_mirror row_mask:0xf bank_mask:0xf bound_ctrl:1
	s_nop 1
	v_add_f32_dpp v34, v34, v34 row_mirror row_mask:0xf bank_mask:0xf bound_ctrl:1
	s_nop 0
	v_readlane_b32 s18, v34, 16
	v_readlane_b32 s19, v34, 48
	v_readlane_b32 s4, v34, 0
	v_readlane_b32 s5, v34, 32
	v_mov_b32_e32 v34, s18
	v_mov_b32_e32 v35, s19
	v_pk_add_f32 v[34:35], s[4:5], v[34:35]
	s_nop 0
	v_add_f32_e32 v34, v34, v35
	v_fmamk_f32 v34, v34, 0x3a800000, v51
	v_mul_f32_e32 v35, 0x4b800000, v34
	v_cmp_gt_f32_e32 vcc, s3, v34
	s_nop 1
	v_cndmask_b32_e32 v34, v34, v35, vcc
	v_rsq_f32_e32 v34, v34
	v_mul_f32_e32 v35, v3, v42
	v_cvt_pk_bf16_f32 v33, v33, v35
	global_store_dwordx2 v[58:59], v[32:33], off sc1
	v_mul_f32_e32 v32, 0x45800000, v34
	v_cndmask_b32_e32 v34, v34, v32, vcc
	v_mul_f32_e32 v28, v28, v34
	v_mul_f32_e32 v29, v29, v34
	v_mul_f32_e32 v28, v12, v28
	v_mul_f32_e32 v29, v13, v29
	v_lshlrev_b64 v[32:33], 11, v[60:61]
	v_cvt_pk_bf16_f32 v28, v28, v29
	v_mul_f32_e32 v29, v30, v34
	v_mul_f32_e32 v24, v24, v34
	v_mul_f32_e32 v25, v25, v34
	v_lshl_add_u64 v[32:33], v[52:53], 0, v[32:33]
	v_mul_f32_e32 v29, v14, v29
	v_mul_f32_e32 v30, v31, v34
	v_mul_f32_e32 v24, v8, v24
	v_mul_f32_e32 v25, v9, v25
	v_mul_f32_e32 v30, v15, v30
	v_cvt_pk_bf16_f32 v29, v29, v30
	global_store_dwordx2 v[32:33], v[28:29], off sc1
	v_cvt_pk_bf16_f32 v24, v24, v25
	v_mul_f32_e32 v25, v26, v34
	v_mul_f32_e32 v20, v20, v34
	v_mul_f32_e32 v21, v21, v34
	v_mul_f32_e32 v25, v10, v25
	v_mul_f32_e32 v26, v27, v34
	v_mul_f32_e32 v20, v4, v20
	v_mul_f32_e32 v21, v5, v21
	v_mul_f32_e32 v26, v11, v26
	v_cvt_pk_bf16_f32 v25, v25, v26
	global_store_dwordx2 v[32:33], v[24:25], off offset:512 sc1
	v_cvt_pk_bf16_f32 v20, v20, v21
	v_mul_f32_e32 v21, v22, v34
	v_mul_f32_e32 v16, v16, v34
	v_mul_f32_e32 v17, v17, v34
	v_mul_f32_e32 v21, v6, v21
	v_mul_f32_e32 v22, v23, v34
	v_mul_f32_e32 v16, v0, v16
	v_mul_f32_e32 v17, v1, v17
	v_mul_f32_e32 v22, v7, v22
	v_cvt_pk_bf16_f32 v21, v21, v22
	global_store_dwordx2 v[32:33], v[20:21], off offset:1024 sc1
	v_cvt_pk_bf16_f32 v16, v16, v17
	v_mul_f32_e32 v17, v18, v34
	v_cmp_lt_i32_e32 vcc, s17, v50
	v_mul_f32_e32 v17, v2, v17
	v_mul_f32_e32 v18, v19, v34
	s_or_b64 s[14:15], vcc, s[14:15]
	v_lshl_add_u64 v[58:59], v[58:59], 0, s[12:13]
	v_mul_f32_e32 v18, v3, v18
	v_cvt_pk_bf16_f32 v17, v17, v18
	global_store_dwordx2 v[32:33], v[16:17], off offset:1536 sc1
	s_andn2_b64 exec, exec, s[14:15]
	s_cbranch_execz .LBB0_79

; __device__ __forceinline__ unsigned cvt_pk_bf16(float lo, float hi) { unsigned r; asm volatile("v_cvt_pk_bf16_f32 %0, %1, %2" : "=v"(r) : "v"(lo), "v"(hi)); return r; }
; __device__ __forceinline__ void p0_prologue(const Params& p, unsigned char* lds) {
;     ...
;             for (int q = 0; q < 4; ++q) { float s = 0.f;
; #pragma unroll
;                 for (int j = 0; j < 4; ++j) s += (v[q][j][0] * v[q][j][0] + v[q][j][1] * v[q][j][1]) + (v[q][j][2] * v[q][j][2] + v[q][j][3] * v[q][j][3]);
;                 const float rstd = rsqrtf(wave_sum(s) * (1.0f / DM) + EPS);
;                 u32x2* o8 = (u32x2*)(XN + (size_t)mm[q] * DM) + lane;
; #pragma unroll
;                 for (int j = 0; j < 4; ++j) { u32x2 o; o.x = cvt_pk_bf16(v[q][j][0] * rstd * gv[j][0], v[q][j][1] * rstd * gv[j][1]); o.y = cvt_pk_bf16(v[q][j][2] * rstd * gv[j][2], v[q][j][3] * rstd * gv[j][3]); __builtin_nontemporal_store(o, o8 + 64 * j); } }
.LBB0_79:
	s_or_b64 exec, exec, s[6:7]
	s_cmp_lg_u32 s66, 0x100
	s_cbranch_scc1 .Lxs_end
	s_cmp_gt_u32 s20, 0x1ff
	s_cbranch_scc1 .Lxs_end
	s_waitcnt vmcnt(16)
	v_mul_f32_e32 v136, v104, v104
	v_fmac_f32_e32 v136, v105, v105
	v_fmac_f32_e32 v136, v106, v106
	v_fmac_f32_e32 v136, v107, v107
	v_fmac_f32_e32 v136, v108, v108
	v_fmac_f32_e32 v136, v109, v109
	v_fmac_f32_e32 v136, v110, v110
	v_fmac_f32_e32 v136, v111, v111
	v_fmac_f32_e32 v136, v112, v112
	v_fmac_f32_e32 v136, v113, v113
	v_fmac_f32_e32 v136, v114, v114
	v_fmac_f32_e32 v136, v115, v115
	v_fmac_f32_e32 v136, v116, v116
	v_fmac_f32_e32 v136, v117, v117
	v_fmac_f32_e32 v136, v118, v118
	v_fmac_f32_e32 v136, v119, v119
	s_nop 1
	v_add_f32_dpp v136, v136, v136 quad_perm:[1,0,3,2] row_mask:0xf bank_mask:0xf bound_ctrl:1
	s_nop 1
	v_add_f32_dpp v136, v136, v136 quad_perm:[2,3,0,1] row_mask:0xf bank_mask:0xf bound_ctrl:1
	s_nop 1
	v_add_f32_dpp v136, v136, v136 row_half_mirror row_mask:0xf bank_mask:0xf bound_ctrl:1
	s_nop 1
	v_add_f32_dpp v136, v136, v136 row_mirror row_mask:0xf bank_mask:0xf bound_ctrl:1
	s_nop 1
	v_readlane_b32 s28, v136, 0
	v_readlane_b32 s29, v136, 16
	v_readlane_b32 s30, v136, 32
	v_readlane_b32 s31, v136, 48
	s_add_i32 s21, s20, 0x4000
	s_lshl_b32 s21, s21, 11
	s_add_u32 s26, s64, s21
	s_addc_u32 s27, s65, 0
	s_add_u32 s26, s26, 0x96f5e00
	s_addc_u32 s27, s27, 0
	v_mov_b32_e32 v138, s29
	v_mov_b32_e32 v139, s31
	v_add_f32_e32 v138, s28, v138
	v_add_f32_e32 v139, s30, v139
	v_add_f32_e32 v138, v138, v139
	v_mov_b32_e32 v139, 0x358637bd
	v_fmac_f32_e32 v139, 0x3a800000, v138
	v_lshlrev_b32_e32 v137, 3, v206
	v_rsq_f32_e32 v139, v139
	s_nop 0
	v_mul_f32_e32 v104, v104, v139
	v_mul_f32_e32 v105, v105, v139
	v_mul_f32_e32 v106, v106, v139
	v_mul_f32_e32 v107, v107, v139
	v_mul_f32_e32 v108, v108, v139
	v_mul_f32_e32 v109, v109, v139
	v_mul_f32_e32 v110, v110, v139
	v_mul_f32_e32 v111, v111, v139
	v_mul_f32_e32 v112, v112, v139
	v_mul_f32_e32 v113, v113, v139
	v_mul_f32_e32 v114, v114, v139
	v_mul_f32_e32 v115, v115, v139
	v_mul_f32_e32 v116, v116, v139
	v_mul_f32_e32 v117, v117, v139
	v_mul_f32_e32 v118, v118, v139
	v_mul_f32_e32 v119, v119, v139
	v_mul_f32_e32 v104, v104, v120
	v_mul_f32_e32 v105, v105, v121
	v_mul_f32_e32 v106, v106, v122
	v_mul_f32_e32 v107, v107, v123
	v_mul_f32_e32 v108, v108, v124
	v_mul_f32_e32 v109, v109, v125
	v_mul_f32_e32 v110, v110, v126
	v_mul_f32_e32 v111, v111, v127
	v_mul_f32_e32 v112, v112, v128
	v_mul_f32_e32 v113, v113, v129
	v_mul_f32_e32 v114, v114, v130
	v_mul_f32_e32 v115, v115, v131
	v_mul_f32_e32 v116, v116, v132
	v_mul_f32_e32 v117, v117, v133
	v_mul_f32_e32 v118, v118, v134
	v_mul_f32_e32 v119, v119, v135
	v_cvt_pk_bf16_f32 v104, v104, v105
	v_cvt_pk_bf16_f32 v105, v106, v107
	global_store_dwordx2 v137, v[104:105], s[26:27] sc1
	v_cvt_pk_bf16_f32 v108, v108, v109
	v_cvt_pk_bf16_f32 v109, v110, v111
	global_store_dwordx2 v137, v[108:109], s[26:27] offset:512 sc1
	v_cvt_pk_bf16_f32 v112, v112, v113
	v_cvt_pk_bf16_f32 v113, v114, v115
	global_store_dwordx2 v137, v[112:113], s[26:27] offset:1024 sc1
	v_cvt_pk_bf16_f32 v116, v116, v117
	v_cvt_pk_bf16_f32 v117, v118, v119
	global_store_dwordx2 v137, v[116:117], s[26:27] offset:1536 sc1
